# static s_setprio 1 for waves 4-7 + w_o/ffn_down residual epilogue: straight-line, x loads of 4 rows batched (rows are always latent)
# speedup vs baseline: 1.0635x; 1.0034x over previous
_Z14fwd_megakernel6Params:
	s_mov_b32 s94, s2
	v_readfirstlane_b32 s4, v0
	s_nop 3
	s_and_b32 s4, s4, 0x3ff
	s_cmp_ge_u32 s4, 0x100
	s_cbranch_scc0 .Lprio_done
	s_setprio 1
.Lprio_done:
	s_add_u32 s2, s0, 0xf8
	s_addc_u32 s3, s1, 0
	s_load_dwordx2 s[36:37], s[0:1], 0xf8
	v_writelane_b32 v255, s2, 0
	v_and_b32_e32 v190, 0x3ff, v0
	v_mov_b32_e32 v1, v190
	v_writelane_b32 v255, s3, 1
	v_writelane_b32 v255, s0, 2
	s_load_dword s33, s[0:1], 0x100
	s_nop 0
	v_writelane_b32 v255, s1, 3
	v_cmp_gt_i32_e32 vcc, 4, v1
	s_and_saveexec_b64 s[0:1], vcc
	v_lshl_add_u32 v1, v1, 2, 0
	v_add_u32_e32 v1, 0x24400, v1
	v_mov_b32_e32 v2, 0
	ds_write_b32 v1, v2
	s_or_b64 exec, exec, s[0:1]
	v_readlane_b32 s0, v255, 2
	v_readlane_b32 s1, v255, 3
	s_waitcnt lgkmcnt(0)
	s_barrier
	s_load_dwordx2 s[0:1], s[0:1], 0xf0
	v_mov_b32_e32 v1, v190
	s_getreg_b32 s4, hwreg(HW_REG_XCC_ID, 0, 4)
	s_waitcnt lgkmcnt(0)
	v_writelane_b32 v255, s0, 4
	v_cmp_eq_u32_e32 vcc, 0, v1
	s_nop 0
	v_writelane_b32 v255, s1, 5
	s_and_saveexec_b64 s[0:1], vcc
	s_cbranch_execz .LBB0_5
	s_mov_b64 s[2:3], exec
	v_mbcnt_lo_u32_b32 v1, s2, 0
	v_mbcnt_hi_u32_b32 v1, s3, v1
	v_cmp_eq_u32_e32 vcc, 0, v1
	s_and_b64 s[6:7], exec, vcc
	s_mov_b64 exec, s[6:7]
	s_cbranch_execz .LBB0_5
	s_lshl_b32 s4, s4, 8
	s_and_b32 s4, s4, 0xf00
	v_readlane_b32 s6, v255, 4
	v_readlane_b32 s7, v255, 5
	s_add_u32 s4, s6, s4
	s_addc_u32 s5, s7, 0
	s_bcnt1_i32_b64 s2, s[2:3]
	v_mov_b32_e32 v1, 0xf37a000
	v_mov_b32_e32 v2, s2
	global_atomic_add v1, v2, s[4:5] offset:1024

.LBB0_662:
	s_or_b64 exec, exec, s[0:1]
	s_mul_hi_i32 s0, s10, 0x3e0f83e1
	s_lshr_b32 s1, s0, 31
	s_ashr_i32 s0, s0, 3
	s_add_i32 s0, s0, s1
	s_mul_hi_i32 s1, s0, 0x6000
	s_mulk_i32 s0, 0x6000
	s_add_u32 s0, s14, s0
	s_addc_u32 s1, s15, s1
	s_add_u32 s10, s0, 0x2000
	v_or_b32_e32 v136, s12, v143
	s_addc_u32 s11, s1, 0
	v_lshlrev_b32_e32 v132, 2, v136
	s_waitcnt lgkmcnt(0)
	s_barrier
	global_load_dwordx4 v[128:131], v132, s[10:11] offset:16
	s_nop 0
	global_load_dwordx4 v[132:135], v132, s[10:11]
	v_add_u32_e32 v137, s13, v144
	s_load_dwordx2 s[24:25], s[40:41], 0xe8
	v_lshlrev_b32_e32 v176, 2, v136
	v_lshrrev_b32_e32 v249, 13, v137
	v_min_u32_e32 v249, 1, v249
	v_lshlrev_b32_e32 v249, 8, v249
	v_sub_u32_e32 v249, v137, v249
	v_lshlrev_b32_e32 v249, 12, v249
	v_lshl_add_u32 v249, v136, 2, v249
	v_add_u32_e32 v248, 0x10000, v145
	s_waitcnt lgkmcnt(0)
	v_mov_b32_e32 v254, v249
	v_add_u32_e32 v253, 0x20000, v249
	v_add_u32_e32 v251, 0x40000, v249
	v_add_u32_e32 v250, 0x60000, v249
	global_load_dwordx4 v[170:173], v254, s[24:25]
	global_load_dwordx4 v[178:181], v254, s[24:25] offset:16
	global_load_dwordx4 v[182:185], v253, s[24:25]
	global_load_dwordx4 v[186:189], v253, s[24:25] offset:16
	global_load_dwordx4 v[192:195], v251, s[24:25]
	global_load_dwordx4 v[198:201], v251, s[24:25] offset:16
	global_load_dwordx4 v[204:207], v250, s[24:25]
	global_load_dwordx4 v[208:211], v250, s[24:25] offset:16
	ds_read_b128 v[212:215], v145
	ds_read_b128 v[216:219], v145 offset:16
	ds_read_b128 v[220:223], v145 offset:16384
	ds_read_b128 v[224:227], v145 offset:16400
	s_waitcnt vmcnt(6)
	v_pk_mul_f32 v[172:173], v[172:173], s[34:35] op_sel_hi:[1,0]
	v_pk_mul_f32 v[170:171], v[170:171], s[34:35] op_sel_hi:[1,0]
	v_pk_mul_f32 v[180:181], v[180:181], s[34:35] op_sel_hi:[1,0]
	v_pk_mul_f32 v[178:179], v[178:179], s[34:35] op_sel_hi:[1,0]
	s_waitcnt lgkmcnt(2)
	v_pk_fma_f32 v[172:173], v[134:135], v[214:215], v[172:173]
	v_pk_fma_f32 v[170:171], v[132:133], v[212:213], v[170:171]
	v_pk_fma_f32 v[180:181], v[130:131], v[218:219], v[180:181]
	v_pk_fma_f32 v[178:179], v[128:129], v[216:217], v[178:179]
	ds_read_b128 v[212:215], v145 offset:32768
	ds_read_b128 v[216:219], v145 offset:32784
	global_store_dwordx4 v254, v[170:173], s[24:25]
	global_store_dwordx4 v254, v[178:181], s[24:25] offset:16
	s_waitcnt vmcnt(6)
	v_pk_mul_f32 v[184:185], v[184:185], s[34:35] op_sel_hi:[1,0]
	v_pk_mul_f32 v[182:183], v[182:183], s[34:35] op_sel_hi:[1,0]
	v_pk_mul_f32 v[188:189], v[188:189], s[34:35] op_sel_hi:[1,0]
	v_pk_mul_f32 v[186:187], v[186:187], s[34:35] op_sel_hi:[1,0]
	s_waitcnt lgkmcnt(2)
	v_pk_fma_f32 v[184:185], v[134:135], v[222:223], v[184:185]
	v_pk_fma_f32 v[182:183], v[132:133], v[220:221], v[182:183]
	v_pk_fma_f32 v[188:189], v[130:131], v[226:227], v[188:189]
	v_pk_fma_f32 v[186:187], v[128:129], v[224:225], v[186:187]
	ds_read_b128 v[220:223], v145 offset:49152
	ds_read_b128 v[224:227], v145 offset:49168
	global_store_dwordx4 v253, v[182:185], s[24:25]
	global_store_dwordx4 v253, v[186:189], s[24:25] offset:16
	s_waitcnt vmcnt(6)
	v_pk_mul_f32 v[194:195], v[194:195], s[34:35] op_sel_hi:[1,0]
	v_pk_mul_f32 v[192:193], v[192:193], s[34:35] op_sel_hi:[1,0]
	v_pk_mul_f32 v[200:201], v[200:201], s[34:35] op_sel_hi:[1,0]
	v_pk_mul_f32 v[198:199], v[198:199], s[34:35] op_sel_hi:[1,0]
	s_waitcnt lgkmcnt(2)
	v_pk_fma_f32 v[194:195], v[134:135], v[214:215], v[194:195]
	v_pk_fma_f32 v[192:193], v[132:133], v[212:213], v[192:193]
	v_pk_fma_f32 v[200:201], v[130:131], v[218:219], v[200:201]
	v_pk_fma_f32 v[198:199], v[128:129], v[216:217], v[198:199]
	global_store_dwordx4 v251, v[192:195], s[24:25]
	global_store_dwordx4 v251, v[198:201], s[24:25] offset:16
	s_waitcnt vmcnt(6)
	v_pk_mul_f32 v[206:207], v[206:207], s[34:35] op_sel_hi:[1,0]
	v_pk_mul_f32 v[204:205], v[204:205], s[34:35] op_sel_hi:[1,0]
	v_pk_mul_f32 v[210:211], v[210:211], s[34:35] op_sel_hi:[1,0]
	v_pk_mul_f32 v[208:209], v[208:209], s[34:35] op_sel_hi:[1,0]
	s_waitcnt lgkmcnt(0)
	v_pk_fma_f32 v[206:207], v[134:135], v[222:223], v[206:207]
	v_pk_fma_f32 v[204:205], v[132:133], v[220:221], v[204:205]
	v_pk_fma_f32 v[210:211], v[130:131], v[226:227], v[210:211]
	v_pk_fma_f32 v[208:209], v[128:129], v[224:225], v[208:209]
	global_store_dwordx4 v250, v[204:207], s[24:25]
	global_store_dwordx4 v250, v[208:211], s[24:25] offset:16
	s_nop 1
	v_add_u32_e32 v254, 0x80000, v249
	v_add_u32_e32 v253, 0xa0000, v249
	v_add_u32_e32 v251, 0xc0000, v249
	v_add_u32_e32 v250, 0xe0000, v249
	global_load_dwordx4 v[170:173], v254, s[24:25]
	global_load_dwordx4 v[178:181], v254, s[24:25] offset:16
	global_load_dwordx4 v[182:185], v253, s[24:25]
	global_load_dwordx4 v[186:189], v253, s[24:25] offset:16
	global_load_dwordx4 v[192:195], v251, s[24:25]
	global_load_dwordx4 v[198:201], v251, s[24:25] offset:16
	global_load_dwordx4 v[204:207], v250, s[24:25]
	global_load_dwordx4 v[208:211], v250, s[24:25] offset:16
	ds_read_b128 v[212:215], v248
	ds_read_b128 v[216:219], v248 offset:16
	ds_read_b128 v[220:223], v248 offset:16384
	ds_read_b128 v[224:227], v248 offset:16400
	s_waitcnt vmcnt(6)
	v_pk_mul_f32 v[172:173], v[172:173], s[34:35] op_sel_hi:[1,0]
	v_pk_mul_f32 v[170:171], v[170:171], s[34:35] op_sel_hi:[1,0]
	v_pk_mul_f32 v[180:181], v[180:181], s[34:35] op_sel_hi:[1,0]
	v_pk_mul_f32 v[178:179], v[178:179], s[34:35] op_sel_hi:[1,0]
	s_waitcnt lgkmcnt(2)
	v_pk_fma_f32 v[172:173], v[134:135], v[214:215], v[172:173]
	v_pk_fma_f32 v[170:171], v[132:133], v[212:213], v[170:171]
	v_pk_fma_f32 v[180:181], v[130:131], v[218:219], v[180:181]
	v_pk_fma_f32 v[178:179], v[128:129], v[216:217], v[178:179]
	ds_read_b128 v[212:215], v248 offset:32768
	ds_read_b128 v[216:219], v248 offset:32784
	global_store_dwordx4 v254, v[170:173], s[24:25]
	global_store_dwordx4 v254, v[178:181], s[24:25] offset:16
	s_waitcnt vmcnt(6)
	v_pk_mul_f32 v[184:185], v[184:185], s[34:35] op_sel_hi:[1,0]
	v_pk_mul_f32 v[182:183], v[182:183], s[34:35] op_sel_hi:[1,0]
	v_pk_mul_f32 v[188:189], v[188:189], s[34:35] op_sel_hi:[1,0]
	v_pk_mul_f32 v[186:187], v[186:187], s[34:35] op_sel_hi:[1,0]
	s_waitcnt lgkmcnt(2)
	v_pk_fma_f32 v[184:185], v[134:135], v[222:223], v[184:185]
	v_pk_fma_f32 v[182:183], v[132:133], v[220:221], v[182:183]
	v_pk_fma_f32 v[188:189], v[130:131], v[226:227], v[188:189]
	v_pk_fma_f32 v[186:187], v[128:129], v[224:225], v[186:187]
	ds_read_b128 v[220:223], v248 offset:49152
	ds_read_b128 v[224:227], v248 offset:49168
	global_store_dwordx4 v253, v[182:185], s[24:25]
	global_store_dwordx4 v253, v[186:189], s[24:25] offset:16
	s_waitcnt vmcnt(6)
	v_pk_mul_f32 v[194:195], v[194:195], s[34:35] op_sel_hi:[1,0]
	v_pk_mul_f32 v[192:193], v[192:193], s[34:35] op_sel_hi:[1,0]
	v_pk_mul_f32 v[200:201], v[200:201], s[34:35] op_sel_hi:[1,0]
	v_pk_mul_f32 v[198:199], v[198:199], s[34:35] op_sel_hi:[1,0]
	s_waitcnt lgkmcnt(2)
	v_pk_fma_f32 v[194:195], v[134:135], v[214:215], v[194:195]
	v_pk_fma_f32 v[192:193], v[132:133], v[212:213], v[192:193]
	v_pk_fma_f32 v[200:201], v[130:131], v[218:219], v[200:201]
	v_pk_fma_f32 v[198:199], v[128:129], v[216:217], v[198:199]
	global_store_dwordx4 v251, v[192:195], s[24:25]
	global_store_dwordx4 v251, v[198:201], s[24:25] offset:16
	s_waitcnt vmcnt(6)
	v_pk_mul_f32 v[206:207], v[206:207], s[34:35] op_sel_hi:[1,0]
	v_pk_mul_f32 v[204:205], v[204:205], s[34:35] op_sel_hi:[1,0]
	v_pk_mul_f32 v[210:211], v[210:211], s[34:35] op_sel_hi:[1,0]
	v_pk_mul_f32 v[208:209], v[208:209], s[34:35] op_sel_hi:[1,0]
	s_waitcnt lgkmcnt(0)
	v_pk_fma_f32 v[206:207], v[134:135], v[222:223], v[206:207]
	v_pk_fma_f32 v[204:205], v[132:133], v[220:221], v[204:205]
	v_pk_fma_f32 v[210:211], v[130:131], v[226:227], v[210:211]
	v_pk_fma_f32 v[208:209], v[128:129], v[224:225], v[208:209]
	global_store_dwordx4 v250, v[204:207], s[24:25]
	global_store_dwordx4 v250, v[208:211], s[24:25] offset:16

.LBB0_674:
	s_or_b64 exec, exec, s[0:1]
	v_lshl_or_b32 v4, v136, 2, v191
	s_waitcnt lgkmcnt(0)
	s_barrier
	global_load_dwordx4 v[0:3], v4, s[10:11] offset:16
	s_nop 0
	global_load_dwordx4 v[4:7], v4, s[10:11]
	s_load_dwordx2 s[24:25], s[40:41], 0xe8
	v_lshlrev_b32_e32 v176, 2, v136
	v_lshrrev_b32_e32 v249, 13, v137
	v_min_u32_e32 v249, 1, v249
	v_lshlrev_b32_e32 v249, 8, v249
	v_sub_u32_e32 v249, v137, v249
	v_lshlrev_b32_e32 v249, 12, v249
	v_lshl_add_u32 v249, v136, 2, v249
	v_add_u32_e32 v248, 0x10000, v145
	s_waitcnt lgkmcnt(0)
	v_mov_b32_e32 v254, v249
	v_add_u32_e32 v253, 0x20000, v249
	v_add_u32_e32 v251, 0x40000, v249
	v_add_u32_e32 v250, 0x60000, v249
	global_load_dwordx4 v[170:173], v254, s[24:25] offset:512
	global_load_dwordx4 v[178:181], v254, s[24:25] offset:528
	global_load_dwordx4 v[182:185], v253, s[24:25] offset:512
	global_load_dwordx4 v[186:189], v253, s[24:25] offset:528
	global_load_dwordx4 v[192:195], v251, s[24:25] offset:512
	global_load_dwordx4 v[198:201], v251, s[24:25] offset:528
	global_load_dwordx4 v[204:207], v250, s[24:25] offset:512
	global_load_dwordx4 v[208:211], v250, s[24:25] offset:528
	ds_read_b128 v[212:215], v145
	ds_read_b128 v[216:219], v145 offset:16
	ds_read_b128 v[220:223], v145 offset:16384
	ds_read_b128 v[224:227], v145 offset:16400
	s_waitcnt vmcnt(6)
	v_pk_mul_f32 v[172:173], v[172:173], s[34:35] op_sel_hi:[1,0]
	v_pk_mul_f32 v[170:171], v[170:171], s[34:35] op_sel_hi:[1,0]
	v_pk_mul_f32 v[180:181], v[180:181], s[34:35] op_sel_hi:[1,0]
	v_pk_mul_f32 v[178:179], v[178:179], s[34:35] op_sel_hi:[1,0]
	s_waitcnt lgkmcnt(2)
	v_pk_fma_f32 v[172:173], v[6:7], v[214:215], v[172:173]
	v_pk_fma_f32 v[170:171], v[4:5], v[212:213], v[170:171]
	v_pk_fma_f32 v[180:181], v[2:3], v[218:219], v[180:181]
	v_pk_fma_f32 v[178:179], v[0:1], v[216:217], v[178:179]
	ds_read_b128 v[212:215], v145 offset:32768
	ds_read_b128 v[216:219], v145 offset:32784
	global_store_dwordx4 v254, v[170:173], s[24:25] offset:512
	global_store_dwordx4 v254, v[178:181], s[24:25] offset:528
	s_waitcnt vmcnt(6)
	v_pk_mul_f32 v[184:185], v[184:185], s[34:35] op_sel_hi:[1,0]
	v_pk_mul_f32 v[182:183], v[182:183], s[34:35] op_sel_hi:[1,0]
	v_pk_mul_f32 v[188:189], v[188:189], s[34:35] op_sel_hi:[1,0]
	v_pk_mul_f32 v[186:187], v[186:187], s[34:35] op_sel_hi:[1,0]
	s_waitcnt lgkmcnt(2)
	v_pk_fma_f32 v[184:185], v[6:7], v[222:223], v[184:185]
	v_pk_fma_f32 v[182:183], v[4:5], v[220:221], v[182:183]
	v_pk_fma_f32 v[188:189], v[2:3], v[226:227], v[188:189]
	v_pk_fma_f32 v[186:187], v[0:1], v[224:225], v[186:187]
	ds_read_b128 v[220:223], v145 offset:49152
	ds_read_b128 v[224:227], v145 offset:49168
	global_store_dwordx4 v253, v[182:185], s[24:25] offset:512
	global_store_dwordx4 v253, v[186:189], s[24:25] offset:528
	s_waitcnt vmcnt(6)
	v_pk_mul_f32 v[194:195], v[194:195], s[34:35] op_sel_hi:[1,0]
	v_pk_mul_f32 v[192:193], v[192:193], s[34:35] op_sel_hi:[1,0]
	v_pk_mul_f32 v[200:201], v[200:201], s[34:35] op_sel_hi:[1,0]
	v_pk_mul_f32 v[198:199], v[198:199], s[34:35] op_sel_hi:[1,0]
	s_waitcnt lgkmcnt(2)
	v_pk_fma_f32 v[194:195], v[6:7], v[214:215], v[194:195]
	v_pk_fma_f32 v[192:193], v[4:5], v[212:213], v[192:193]
	v_pk_fma_f32 v[200:201], v[2:3], v[218:219], v[200:201]
	v_pk_fma_f32 v[198:199], v[0:1], v[216:217], v[198:199]
	global_store_dwordx4 v251, v[192:195], s[24:25] offset:512
	global_store_dwordx4 v251, v[198:201], s[24:25] offset:528
	s_waitcnt vmcnt(6)
	v_pk_mul_f32 v[206:207], v[206:207], s[34:35] op_sel_hi:[1,0]
	v_pk_mul_f32 v[204:205], v[204:205], s[34:35] op_sel_hi:[1,0]
	v_pk_mul_f32 v[210:211], v[210:211], s[34:35] op_sel_hi:[1,0]
	v_pk_mul_f32 v[208:209], v[208:209], s[34:35] op_sel_hi:[1,0]
	s_waitcnt lgkmcnt(0)
	v_pk_fma_f32 v[206:207], v[6:7], v[222:223], v[206:207]
	v_pk_fma_f32 v[204:205], v[4:5], v[220:221], v[204:205]
	v_pk_fma_f32 v[210:211], v[2:3], v[226:227], v[210:211]
	v_pk_fma_f32 v[208:209], v[0:1], v[224:225], v[208:209]
	global_store_dwordx4 v250, v[204:207], s[24:25] offset:512
	global_store_dwordx4 v250, v[208:211], s[24:25] offset:528
	s_nop 1
	v_add_u32_e32 v254, 0x80000, v249
	v_add_u32_e32 v253, 0xa0000, v249
	v_add_u32_e32 v251, 0xc0000, v249
	v_add_u32_e32 v250, 0xe0000, v249
	global_load_dwordx4 v[170:173], v254, s[24:25] offset:512
	global_load_dwordx4 v[178:181], v254, s[24:25] offset:528
	global_load_dwordx4 v[182:185], v253, s[24:25] offset:512
	global_load_dwordx4 v[186:189], v253, s[24:25] offset:528
	global_load_dwordx4 v[192:195], v251, s[24:25] offset:512
	global_load_dwordx4 v[198:201], v251, s[24:25] offset:528
	global_load_dwordx4 v[204:207], v250, s[24:25] offset:512
	global_load_dwordx4 v[208:211], v250, s[24:25] offset:528
	ds_read_b128 v[212:215], v248
	ds_read_b128 v[216:219], v248 offset:16
	ds_read_b128 v[220:223], v248 offset:16384
	ds_read_b128 v[224:227], v248 offset:16400
	s_waitcnt vmcnt(6)
	v_pk_mul_f32 v[172:173], v[172:173], s[34:35] op_sel_hi:[1,0]
	v_pk_mul_f32 v[170:171], v[170:171], s[34:35] op_sel_hi:[1,0]
	v_pk_mul_f32 v[180:181], v[180:181], s[34:35] op_sel_hi:[1,0]
	v_pk_mul_f32 v[178:179], v[178:179], s[34:35] op_sel_hi:[1,0]
	s_waitcnt lgkmcnt(2)
	v_pk_fma_f32 v[172:173], v[6:7], v[214:215], v[172:173]
	v_pk_fma_f32 v[170:171], v[4:5], v[212:213], v[170:171]
	v_pk_fma_f32 v[180:181], v[2:3], v[218:219], v[180:181]
	v_pk_fma_f32 v[178:179], v[0:1], v[216:217], v[178:179]
	ds_read_b128 v[212:215], v248 offset:32768
	ds_read_b128 v[216:219], v248 offset:32784
	global_store_dwordx4 v254, v[170:173], s[24:25] offset:512
	global_store_dwordx4 v254, v[178:181], s[24:25] offset:528
	s_waitcnt vmcnt(6)
	v_pk_mul_f32 v[184:185], v[184:185], s[34:35] op_sel_hi:[1,0]
	v_pk_mul_f32 v[182:183], v[182:183], s[34:35] op_sel_hi:[1,0]
	v_pk_mul_f32 v[188:189], v[188:189], s[34:35] op_sel_hi:[1,0]
	v_pk_mul_f32 v[186:187], v[186:187], s[34:35] op_sel_hi:[1,0]
	s_waitcnt lgkmcnt(2)
	v_pk_fma_f32 v[184:185], v[6:7], v[222:223], v[184:185]
	v_pk_fma_f32 v[182:183], v[4:5], v[220:221], v[182:183]
	v_pk_fma_f32 v[188:189], v[2:3], v[226:227], v[188:189]
	v_pk_fma_f32 v[186:187], v[0:1], v[224:225], v[186:187]
	ds_read_b128 v[220:223], v248 offset:49152
	ds_read_b128 v[224:227], v248 offset:49168
	global_store_dwordx4 v253, v[182:185], s[24:25] offset:512
	global_store_dwordx4 v253, v[186:189], s[24:25] offset:528
	s_waitcnt vmcnt(6)
	v_pk_mul_f32 v[194:195], v[194:195], s[34:35] op_sel_hi:[1,0]
	v_pk_mul_f32 v[192:193], v[192:193], s[34:35] op_sel_hi:[1,0]
	v_pk_mul_f32 v[200:201], v[200:201], s[34:35] op_sel_hi:[1,0]
	v_pk_mul_f32 v[198:199], v[198:199], s[34:35] op_sel_hi:[1,0]
	s_waitcnt lgkmcnt(2)
	v_pk_fma_f32 v[194:195], v[6:7], v[214:215], v[194:195]
	v_pk_fma_f32 v[192:193], v[4:5], v[212:213], v[192:193]
	v_pk_fma_f32 v[200:201], v[2:3], v[218:219], v[200:201]
	v_pk_fma_f32 v[198:199], v[0:1], v[216:217], v[198:199]
	global_store_dwordx4 v251, v[192:195], s[24:25] offset:512
	global_store_dwordx4 v251, v[198:201], s[24:25] offset:528
	s_waitcnt vmcnt(6)
	v_pk_mul_f32 v[206:207], v[206:207], s[34:35] op_sel_hi:[1,0]
	v_pk_mul_f32 v[204:205], v[204:205], s[34:35] op_sel_hi:[1,0]
	v_pk_mul_f32 v[210:211], v[210:211], s[34:35] op_sel_hi:[1,0]
	v_pk_mul_f32 v[208:209], v[208:209], s[34:35] op_sel_hi:[1,0]
	s_waitcnt lgkmcnt(0)
	v_pk_fma_f32 v[206:207], v[6:7], v[222:223], v[206:207]
	v_pk_fma_f32 v[204:205], v[4:5], v[220:221], v[204:205]
	v_pk_fma_f32 v[210:211], v[2:3], v[226:227], v[210:211]
	v_pk_fma_f32 v[208:209], v[0:1], v[224:225], v[208:209]
	global_store_dwordx4 v250, v[204:207], s[24:25] offset:512
	global_store_dwordx4 v250, v[208:211], s[24:25] offset:528
	s_branch .LBB0_655

.LBB0_1146:
	s_or_b64 exec, exec, s[10:11]
	s_mul_hi_i32 s2, s13, 0x3e0f83e1
	s_lshr_b32 s3, s2, 31
	s_ashr_i32 s2, s2, 3
	s_add_i32 s2, s2, s3
	s_mul_hi_i32 s3, s2, 0x6000
	s_mulk_i32 s2, 0x6000
	s_add_u32 s2, s14, s2
	s_addc_u32 s3, s15, s3
	s_add_u32 s10, s2, 0x5000
	v_or_b32_e32 v136, s12, v143
	s_addc_u32 s11, s3, 0
	v_lshlrev_b32_e32 v132, 2, v136
	s_waitcnt lgkmcnt(0)
	s_barrier
	global_load_dwordx4 v[128:131], v132, s[10:11] offset:16
	s_nop 0
	global_load_dwordx4 v[132:135], v132, s[10:11]
	v_add_u32_e32 v137, s18, v144
	s_load_dwordx2 s[24:25], s[0:1], 0xe8
	v_lshlrev_b32_e32 v176, 2, v136
	v_lshrrev_b32_e32 v249, 13, v137
	v_min_u32_e32 v249, 1, v249
	v_lshlrev_b32_e32 v249, 8, v249
	v_sub_u32_e32 v249, v137, v249
	v_lshlrev_b32_e32 v249, 12, v249
	v_lshl_add_u32 v249, v136, 2, v249
	v_add_u32_e32 v248, 0x10000, v145
	s_waitcnt lgkmcnt(0)
	v_mov_b32_e32 v254, v249
	v_add_u32_e32 v253, 0x20000, v249
	v_add_u32_e32 v251, 0x40000, v249
	v_add_u32_e32 v250, 0x60000, v249
	global_load_dwordx4 v[170:173], v254, s[24:25]
	global_load_dwordx4 v[178:181], v254, s[24:25] offset:16
	global_load_dwordx4 v[182:185], v253, s[24:25]
	global_load_dwordx4 v[186:189], v253, s[24:25] offset:16
	global_load_dwordx4 v[192:195], v251, s[24:25]
	global_load_dwordx4 v[198:201], v251, s[24:25] offset:16
	global_load_dwordx4 v[204:207], v250, s[24:25]
	global_load_dwordx4 v[208:211], v250, s[24:25] offset:16
	ds_read_b128 v[212:215], v145
	ds_read_b128 v[216:219], v145 offset:16
	ds_read_b128 v[220:223], v145 offset:16384
	ds_read_b128 v[224:227], v145 offset:16400
	s_waitcnt vmcnt(6)
	v_pk_mul_f32 v[172:173], v[172:173], s[34:35] op_sel_hi:[1,0]
	v_pk_mul_f32 v[170:171], v[170:171], s[34:35] op_sel_hi:[1,0]
	v_pk_mul_f32 v[180:181], v[180:181], s[34:35] op_sel_hi:[1,0]
	v_pk_mul_f32 v[178:179], v[178:179], s[34:35] op_sel_hi:[1,0]
	s_waitcnt lgkmcnt(2)
	v_pk_fma_f32 v[172:173], v[134:135], v[214:215], v[172:173]
	v_pk_fma_f32 v[170:171], v[132:133], v[212:213], v[170:171]
	v_pk_fma_f32 v[180:181], v[130:131], v[218:219], v[180:181]
	v_pk_fma_f32 v[178:179], v[128:129], v[216:217], v[178:179]
	ds_read_b128 v[212:215], v145 offset:32768
	ds_read_b128 v[216:219], v145 offset:32784
	global_store_dwordx4 v254, v[170:173], s[24:25]
	global_store_dwordx4 v254, v[178:181], s[24:25] offset:16
	s_waitcnt vmcnt(6)
	v_pk_mul_f32 v[184:185], v[184:185], s[34:35] op_sel_hi:[1,0]
	v_pk_mul_f32 v[182:183], v[182:183], s[34:35] op_sel_hi:[1,0]
	v_pk_mul_f32 v[188:189], v[188:189], s[34:35] op_sel_hi:[1,0]
	v_pk_mul_f32 v[186:187], v[186:187], s[34:35] op_sel_hi:[1,0]
	s_waitcnt lgkmcnt(2)
	v_pk_fma_f32 v[184:185], v[134:135], v[222:223], v[184:185]
	v_pk_fma_f32 v[182:183], v[132:133], v[220:221], v[182:183]
	v_pk_fma_f32 v[188:189], v[130:131], v[226:227], v[188:189]
	v_pk_fma_f32 v[186:187], v[128:129], v[224:225], v[186:187]
	ds_read_b128 v[220:223], v145 offset:49152
	ds_read_b128 v[224:227], v145 offset:49168
	global_store_dwordx4 v253, v[182:185], s[24:25]
	global_store_dwordx4 v253, v[186:189], s[24:25] offset:16
	s_waitcnt vmcnt(6)
	v_pk_mul_f32 v[194:195], v[194:195], s[34:35] op_sel_hi:[1,0]
	v_pk_mul_f32 v[192:193], v[192:193], s[34:35] op_sel_hi:[1,0]
	v_pk_mul_f32 v[200:201], v[200:201], s[34:35] op_sel_hi:[1,0]
	v_pk_mul_f32 v[198:199], v[198:199], s[34:35] op_sel_hi:[1,0]
	s_waitcnt lgkmcnt(2)
	v_pk_fma_f32 v[194:195], v[134:135], v[214:215], v[194:195]
	v_pk_fma_f32 v[192:193], v[132:133], v[212:213], v[192:193]
	v_pk_fma_f32 v[200:201], v[130:131], v[218:219], v[200:201]
	v_pk_fma_f32 v[198:199], v[128:129], v[216:217], v[198:199]
	global_store_dwordx4 v251, v[192:195], s[24:25]
	global_store_dwordx4 v251, v[198:201], s[24:25] offset:16
	s_waitcnt vmcnt(6)
	v_pk_mul_f32 v[206:207], v[206:207], s[34:35] op_sel_hi:[1,0]
	v_pk_mul_f32 v[204:205], v[204:205], s[34:35] op_sel_hi:[1,0]
	v_pk_mul_f32 v[210:211], v[210:211], s[34:35] op_sel_hi:[1,0]
	v_pk_mul_f32 v[208:209], v[208:209], s[34:35] op_sel_hi:[1,0]
	s_waitcnt lgkmcnt(0)
	v_pk_fma_f32 v[206:207], v[134:135], v[222:223], v[206:207]
	v_pk_fma_f32 v[204:205], v[132:133], v[220:221], v[204:205]
	v_pk_fma_f32 v[210:211], v[130:131], v[226:227], v[210:211]
	v_pk_fma_f32 v[208:209], v[128:129], v[224:225], v[208:209]
	global_store_dwordx4 v250, v[204:207], s[24:25]
	global_store_dwordx4 v250, v[208:211], s[24:25] offset:16
	s_nop 1
	v_add_u32_e32 v254, 0x80000, v249
	v_add_u32_e32 v253, 0xa0000, v249
	v_add_u32_e32 v251, 0xc0000, v249
	v_add_u32_e32 v250, 0xe0000, v249
	global_load_dwordx4 v[170:173], v254, s[24:25]
	global_load_dwordx4 v[178:181], v254, s[24:25] offset:16
	global_load_dwordx4 v[182:185], v253, s[24:25]
	global_load_dwordx4 v[186:189], v253, s[24:25] offset:16
	global_load_dwordx4 v[192:195], v251, s[24:25]
	global_load_dwordx4 v[198:201], v251, s[24:25] offset:16
	global_load_dwordx4 v[204:207], v250, s[24:25]
	global_load_dwordx4 v[208:211], v250, s[24:25] offset:16
	ds_read_b128 v[212:215], v248
	ds_read_b128 v[216:219], v248 offset:16
	ds_read_b128 v[220:223], v248 offset:16384
	ds_read_b128 v[224:227], v248 offset:16400
	s_waitcnt vmcnt(6)
	v_pk_mul_f32 v[172:173], v[172:173], s[34:35] op_sel_hi:[1,0]
	v_pk_mul_f32 v[170:171], v[170:171], s[34:35] op_sel_hi:[1,0]
	v_pk_mul_f32 v[180:181], v[180:181], s[34:35] op_sel_hi:[1,0]
	v_pk_mul_f32 v[178:179], v[178:179], s[34:35] op_sel_hi:[1,0]
	s_waitcnt lgkmcnt(2)
	v_pk_fma_f32 v[172:173], v[134:135], v[214:215], v[172:173]
	v_pk_fma_f32 v[170:171], v[132:133], v[212:213], v[170:171]
	v_pk_fma_f32 v[180:181], v[130:131], v[218:219], v[180:181]
	v_pk_fma_f32 v[178:179], v[128:129], v[216:217], v[178:179]
	ds_read_b128 v[212:215], v248 offset:32768
	ds_read_b128 v[216:219], v248 offset:32784
	global_store_dwordx4 v254, v[170:173], s[24:25]
	global_store_dwordx4 v254, v[178:181], s[24:25] offset:16
	s_waitcnt vmcnt(6)
	v_pk_mul_f32 v[184:185], v[184:185], s[34:35] op_sel_hi:[1,0]
	v_pk_mul_f32 v[182:183], v[182:183], s[34:35] op_sel_hi:[1,0]
	v_pk_mul_f32 v[188:189], v[188:189], s[34:35] op_sel_hi:[1,0]
	v_pk_mul_f32 v[186:187], v[186:187], s[34:35] op_sel_hi:[1,0]
	s_waitcnt lgkmcnt(2)
	v_pk_fma_f32 v[184:185], v[134:135], v[222:223], v[184:185]
	v_pk_fma_f32 v[182:183], v[132:133], v[220:221], v[182:183]
	v_pk_fma_f32 v[188:189], v[130:131], v[226:227], v[188:189]
	v_pk_fma_f32 v[186:187], v[128:129], v[224:225], v[186:187]
	ds_read_b128 v[220:223], v248 offset:49152
	ds_read_b128 v[224:227], v248 offset:49168
	global_store_dwordx4 v253, v[182:185], s[24:25]
	global_store_dwordx4 v253, v[186:189], s[24:25] offset:16
	s_waitcnt vmcnt(6)
	v_pk_mul_f32 v[194:195], v[194:195], s[34:35] op_sel_hi:[1,0]
	v_pk_mul_f32 v[192:193], v[192:193], s[34:35] op_sel_hi:[1,0]
	v_pk_mul_f32 v[200:201], v[200:201], s[34:35] op_sel_hi:[1,0]
	v_pk_mul_f32 v[198:199], v[198:199], s[34:35] op_sel_hi:[1,0]
	s_waitcnt lgkmcnt(2)
	v_pk_fma_f32 v[194:195], v[134:135], v[214:215], v[194:195]
	v_pk_fma_f32 v[192:193], v[132:133], v[212:213], v[192:193]
	v_pk_fma_f32 v[200:201], v[130:131], v[218:219], v[200:201]
	v_pk_fma_f32 v[198:199], v[128:129], v[216:217], v[198:199]
	global_store_dwordx4 v251, v[192:195], s[24:25]
	global_store_dwordx4 v251, v[198:201], s[24:25] offset:16
	s_waitcnt vmcnt(6)
	v_pk_mul_f32 v[206:207], v[206:207], s[34:35] op_sel_hi:[1,0]
	v_pk_mul_f32 v[204:205], v[204:205], s[34:35] op_sel_hi:[1,0]
	v_pk_mul_f32 v[210:211], v[210:211], s[34:35] op_sel_hi:[1,0]
	v_pk_mul_f32 v[208:209], v[208:209], s[34:35] op_sel_hi:[1,0]
	s_waitcnt lgkmcnt(0)
	v_pk_fma_f32 v[206:207], v[134:135], v[222:223], v[206:207]
	v_pk_fma_f32 v[204:205], v[132:133], v[220:221], v[204:205]
	v_pk_fma_f32 v[210:211], v[130:131], v[226:227], v[210:211]
	v_pk_fma_f32 v[208:209], v[128:129], v[224:225], v[208:209]
	global_store_dwordx4 v250, v[204:207], s[24:25]
	global_store_dwordx4 v250, v[208:211], s[24:25] offset:16

.LBB0_1158:
	s_or_b64 exec, exec, s[2:3]
	v_lshl_or_b32 v4, v136, 2, v191
	s_waitcnt lgkmcnt(0)
	s_barrier
	global_load_dwordx4 v[0:3], v4, s[10:11] offset:16
	s_nop 0
	global_load_dwordx4 v[4:7], v4, s[10:11]
	s_load_dwordx2 s[24:25], s[0:1], 0xe8
	v_lshlrev_b32_e32 v176, 2, v136
	v_lshrrev_b32_e32 v249, 13, v137
	v_min_u32_e32 v249, 1, v249
	v_lshlrev_b32_e32 v249, 8, v249
	v_sub_u32_e32 v249, v137, v249
	v_lshlrev_b32_e32 v249, 12, v249
	v_lshl_add_u32 v249, v136, 2, v249
	v_add_u32_e32 v248, 0x10000, v145
	s_waitcnt lgkmcnt(0)
	v_mov_b32_e32 v254, v249
	v_add_u32_e32 v253, 0x20000, v249
	v_add_u32_e32 v251, 0x40000, v249
	v_add_u32_e32 v250, 0x60000, v249
	global_load_dwordx4 v[170:173], v254, s[24:25] offset:512
	global_load_dwordx4 v[178:181], v254, s[24:25] offset:528
	global_load_dwordx4 v[182:185], v253, s[24:25] offset:512
	global_load_dwordx4 v[186:189], v253, s[24:25] offset:528
	global_load_dwordx4 v[192:195], v251, s[24:25] offset:512
	global_load_dwordx4 v[198:201], v251, s[24:25] offset:528
	global_load_dwordx4 v[204:207], v250, s[24:25] offset:512
	global_load_dwordx4 v[208:211], v250, s[24:25] offset:528
	ds_read_b128 v[212:215], v145
	ds_read_b128 v[216:219], v145 offset:16
	ds_read_b128 v[220:223], v145 offset:16384
	ds_read_b128 v[224:227], v145 offset:16400
	s_waitcnt vmcnt(6)
	v_pk_mul_f32 v[172:173], v[172:173], s[34:35] op_sel_hi:[1,0]
	v_pk_mul_f32 v[170:171], v[170:171], s[34:35] op_sel_hi:[1,0]
	v_pk_mul_f32 v[180:181], v[180:181], s[34:35] op_sel_hi:[1,0]
	v_pk_mul_f32 v[178:179], v[178:179], s[34:35] op_sel_hi:[1,0]
	s_waitcnt lgkmcnt(2)
	v_pk_fma_f32 v[172:173], v[6:7], v[214:215], v[172:173]
	v_pk_fma_f32 v[170:171], v[4:5], v[212:213], v[170:171]
	v_pk_fma_f32 v[180:181], v[2:3], v[218:219], v[180:181]
	v_pk_fma_f32 v[178:179], v[0:1], v[216:217], v[178:179]
	ds_read_b128 v[212:215], v145 offset:32768
	ds_read_b128 v[216:219], v145 offset:32784
	global_store_dwordx4 v254, v[170:173], s[24:25] offset:512
	global_store_dwordx4 v254, v[178:181], s[24:25] offset:528
	s_waitcnt vmcnt(6)
	v_pk_mul_f32 v[184:185], v[184:185], s[34:35] op_sel_hi:[1,0]
	v_pk_mul_f32 v[182:183], v[182:183], s[34:35] op_sel_hi:[1,0]
	v_pk_mul_f32 v[188:189], v[188:189], s[34:35] op_sel_hi:[1,0]
	v_pk_mul_f32 v[186:187], v[186:187], s[34:35] op_sel_hi:[1,0]
	s_waitcnt lgkmcnt(2)
	v_pk_fma_f32 v[184:185], v[6:7], v[222:223], v[184:185]
	v_pk_fma_f32 v[182:183], v[4:5], v[220:221], v[182:183]
	v_pk_fma_f32 v[188:189], v[2:3], v[226:227], v[188:189]
	v_pk_fma_f32 v[186:187], v[0:1], v[224:225], v[186:187]
	ds_read_b128 v[220:223], v145 offset:49152
	ds_read_b128 v[224:227], v145 offset:49168
	global_store_dwordx4 v253, v[182:185], s[24:25] offset:512
	global_store_dwordx4 v253, v[186:189], s[24:25] offset:528
	s_waitcnt vmcnt(6)
	v_pk_mul_f32 v[194:195], v[194:195], s[34:35] op_sel_hi:[1,0]
	v_pk_mul_f32 v[192:193], v[192:193], s[34:35] op_sel_hi:[1,0]
	v_pk_mul_f32 v[200:201], v[200:201], s[34:35] op_sel_hi:[1,0]
	v_pk_mul_f32 v[198:199], v[198:199], s[34:35] op_sel_hi:[1,0]
	s_waitcnt lgkmcnt(2)
	v_pk_fma_f32 v[194:195], v[6:7], v[214:215], v[194:195]
	v_pk_fma_f32 v[192:193], v[4:5], v[212:213], v[192:193]
	v_pk_fma_f32 v[200:201], v[2:3], v[218:219], v[200:201]
	v_pk_fma_f32 v[198:199], v[0:1], v[216:217], v[198:199]
	global_store_dwordx4 v251, v[192:195], s[24:25] offset:512
	global_store_dwordx4 v251, v[198:201], s[24:25] offset:528
	s_waitcnt vmcnt(6)
	v_pk_mul_f32 v[206:207], v[206:207], s[34:35] op_sel_hi:[1,0]
	v_pk_mul_f32 v[204:205], v[204:205], s[34:35] op_sel_hi:[1,0]
	v_pk_mul_f32 v[210:211], v[210:211], s[34:35] op_sel_hi:[1,0]
	v_pk_mul_f32 v[208:209], v[208:209], s[34:35] op_sel_hi:[1,0]
	s_waitcnt lgkmcnt(0)
	v_pk_fma_f32 v[206:207], v[6:7], v[222:223], v[206:207]
	v_pk_fma_f32 v[204:205], v[4:5], v[220:221], v[204:205]
	v_pk_fma_f32 v[210:211], v[2:3], v[226:227], v[210:211]
	v_pk_fma_f32 v[208:209], v[0:1], v[224:225], v[208:209]
	global_store_dwordx4 v250, v[204:207], s[24:25] offset:512
	global_store_dwordx4 v250, v[208:211], s[24:25] offset:528
	s_nop 1
	v_add_u32_e32 v254, 0x80000, v249
	v_add_u32_e32 v253, 0xa0000, v249
	v_add_u32_e32 v251, 0xc0000, v249
	v_add_u32_e32 v250, 0xe0000, v249
	global_load_dwordx4 v[170:173], v254, s[24:25] offset:512
	global_load_dwordx4 v[178:181], v254, s[24:25] offset:528
	global_load_dwordx4 v[182:185], v253, s[24:25] offset:512
	global_load_dwordx4 v[186:189], v253, s[24:25] offset:528
	global_load_dwordx4 v[192:195], v251, s[24:25] offset:512
	global_load_dwordx4 v[198:201], v251, s[24:25] offset:528
	global_load_dwordx4 v[204:207], v250, s[24:25] offset:512
	global_load_dwordx4 v[208:211], v250, s[24:25] offset:528
	ds_read_b128 v[212:215], v248
	ds_read_b128 v[216:219], v248 offset:16
	ds_read_b128 v[220:223], v248 offset:16384
	ds_read_b128 v[224:227], v248 offset:16400
	s_waitcnt vmcnt(6)
	v_pk_mul_f32 v[172:173], v[172:173], s[34:35] op_sel_hi:[1,0]
	v_pk_mul_f32 v[170:171], v[170:171], s[34:35] op_sel_hi:[1,0]
	v_pk_mul_f32 v[180:181], v[180:181], s[34:35] op_sel_hi:[1,0]
	v_pk_mul_f32 v[178:179], v[178:179], s[34:35] op_sel_hi:[1,0]
	s_waitcnt lgkmcnt(2)
	v_pk_fma_f32 v[172:173], v[6:7], v[214:215], v[172:173]
	v_pk_fma_f32 v[170:171], v[4:5], v[212:213], v[170:171]
	v_pk_fma_f32 v[180:181], v[2:3], v[218:219], v[180:181]
	v_pk_fma_f32 v[178:179], v[0:1], v[216:217], v[178:179]
	ds_read_b128 v[212:215], v248 offset:32768
	ds_read_b128 v[216:219], v248 offset:32784
	global_store_dwordx4 v254, v[170:173], s[24:25] offset:512
	global_store_dwordx4 v254, v[178:181], s[24:25] offset:528
	s_waitcnt vmcnt(6)
	v_pk_mul_f32 v[184:185], v[184:185], s[34:35] op_sel_hi:[1,0]
	v_pk_mul_f32 v[182:183], v[182:183], s[34:35] op_sel_hi:[1,0]
	v_pk_mul_f32 v[188:189], v[188:189], s[34:35] op_sel_hi:[1,0]
	v_pk_mul_f32 v[186:187], v[186:187], s[34:35] op_sel_hi:[1,0]
	s_waitcnt lgkmcnt(2)
	v_pk_fma_f32 v[184:185], v[6:7], v[222:223], v[184:185]
	v_pk_fma_f32 v[182:183], v[4:5], v[220:221], v[182:183]
	v_pk_fma_f32 v[188:189], v[2:3], v[226:227], v[188:189]
	v_pk_fma_f32 v[186:187], v[0:1], v[224:225], v[186:187]
	ds_read_b128 v[220:223], v248 offset:49152
	ds_read_b128 v[224:227], v248 offset:49168
	global_store_dwordx4 v253, v[182:185], s[24:25] offset:512
	global_store_dwordx4 v253, v[186:189], s[24:25] offset:528
	s_waitcnt vmcnt(6)
	v_pk_mul_f32 v[194:195], v[194:195], s[34:35] op_sel_hi:[1,0]
	v_pk_mul_f32 v[192:193], v[192:193], s[34:35] op_sel_hi:[1,0]
	v_pk_mul_f32 v[200:201], v[200:201], s[34:35] op_sel_hi:[1,0]
	v_pk_mul_f32 v[198:199], v[198:199], s[34:35] op_sel_hi:[1,0]
	s_waitcnt lgkmcnt(2)
	v_pk_fma_f32 v[194:195], v[6:7], v[214:215], v[194:195]
	v_pk_fma_f32 v[192:193], v[4:5], v[212:213], v[192:193]
	v_pk_fma_f32 v[200:201], v[2:3], v[218:219], v[200:201]
	v_pk_fma_f32 v[198:199], v[0:1], v[216:217], v[198:199]
	global_store_dwordx4 v251, v[192:195], s[24:25] offset:512
	global_store_dwordx4 v251, v[198:201], s[24:25] offset:528
	s_waitcnt vmcnt(6)
	v_pk_mul_f32 v[206:207], v[206:207], s[34:35] op_sel_hi:[1,0]
	v_pk_mul_f32 v[204:205], v[204:205], s[34:35] op_sel_hi:[1,0]
	v_pk_mul_f32 v[210:211], v[210:211], s[34:35] op_sel_hi:[1,0]
	v_pk_mul_f32 v[208:209], v[208:209], s[34:35] op_sel_hi:[1,0]
	s_waitcnt lgkmcnt(0)
	v_pk_fma_f32 v[206:207], v[6:7], v[222:223], v[206:207]
	v_pk_fma_f32 v[204:205], v[4:5], v[220:221], v[204:205]
	v_pk_fma_f32 v[210:211], v[2:3], v[226:227], v[210:211]
	v_pk_fma_f32 v[208:209], v[0:1], v[224:225], v[208:209]
	global_store_dwordx4 v250, v[204:207], s[24:25] offset:512
	global_store_dwordx4 v250, v[208:211], s[24:25] offset:528
	s_branch .LBB0_1139
